# decode attention: shifted cache rows stored with the default cache policy instead of nt
# baseline (speedup 1.0000x reference)
.LBB0_380:
	v_min_i32_e32 v0, v83, v108
	v_sub_u32_e32 v0, 0x80, v0
	v_add_u32_e32 v123, 1, v83
	v_lshl_add_u32 v6, v0, v111, v85
	v_min_i32_e32 v0, v123, v108
	v_sub_u32_e32 v0, 0x80, v0
	v_add_u32_e32 v122, 2, v83
	v_lshl_add_u32 v8, v0, v111, v85
	v_min_i32_e32 v0, v122, v108
	v_sub_u32_e32 v0, 0x80, v0
	v_add_u32_e32 v117, 3, v83
	v_lshl_add_u32 v10, v0, v111, v85
	v_min_i32_e32 v0, v117, v108
	v_ashrrev_i32_e32 v7, 31, v6
	v_sub_u32_e32 v0, 0x80, v0
	v_add_u32_e32 v116, 4, v83
	v_lshlrev_b64 v[6:7], 11, v[6:7]
	v_ashrrev_i32_e32 v9, 31, v8
	v_lshl_add_u32 v12, v0, v111, v85
	v_min_i32_e32 v0, v116, v108
	v_lshl_add_u64 v[6:7], v[92:93], 0, v[6:7]
	v_lshlrev_b64 v[8:9], 11, v[8:9]
	v_sub_u32_e32 v0, 0x80, v0
	v_add_u32_e32 v115, 5, v83
	global_load_dwordx4 v[66:69], v[6:7], off
	v_lshl_add_u64 v[8:9], v[92:93], 0, v[8:9]
	v_lshl_add_u32 v14, v0, v111, v85
	v_min_i32_e32 v0, v115, v108
	global_load_dwordx4 v[62:65], v[8:9], off
	v_sub_u32_e32 v0, 0x80, v0
	v_add_u32_e32 v114, 6, v83
	v_ashrrev_i32_e32 v11, 31, v10
	v_ashrrev_i32_e32 v13, 31, v12
	v_lshl_add_u32 v16, v0, v111, v85
	v_min_i32_e32 v0, v114, v108
	v_lshlrev_b64 v[10:11], 11, v[10:11]
	v_lshlrev_b64 v[12:13], 11, v[12:13]
	v_sub_u32_e32 v0, 0x80, v0
	v_lshl_add_u64 v[10:11], v[92:93], 0, v[10:11]
	v_lshl_add_u64 v[12:13], v[92:93], 0, v[12:13]
	v_lshl_add_u32 v18, v0, v111, v85
	global_load_dwordx4 v[58:61], v[10:11], off
	global_load_dwordx4 v[54:57], v[12:13], off
	v_ashrrev_i32_e32 v15, 31, v14
	v_ashrrev_i32_e32 v17, 31, v16
	v_ashrrev_i32_e32 v19, 31, v18
	v_lshlrev_b64 v[14:15], 11, v[14:15]
	v_lshlrev_b64 v[16:17], 11, v[16:17]
	v_lshlrev_b64 v[18:19], 11, v[18:19]
	v_lshl_add_u64 v[14:15], v[92:93], 0, v[14:15]
	v_lshl_add_u64 v[16:17], v[92:93], 0, v[16:17]
	v_lshl_add_u64 v[96:97], v[92:93], 0, v[18:19]
	global_load_dwordx4 v[50:53], v[14:15], off
	global_load_dwordx4 v[46:49], v[16:17], off
	global_load_dwordx4 v[42:45], v[96:97], off
	v_add_u32_e32 v113, 7, v83
	v_min_i32_e32 v0, v113, v108
	v_sub_u32_e32 v0, 0x80, v0
	v_lshl_add_u32 v18, v0, v111, v85
	v_ashrrev_i32_e32 v19, 31, v18
	v_lshlrev_b64 v[18:19], 11, v[18:19]
	v_lshl_add_u64 v[98:99], v[92:93], 0, v[18:19]
	global_load_dwordx4 v[38:41], v[98:99], off
	global_load_dwordx4 v[34:37], v[6:7], off offset:1024
	global_load_dwordx4 v[30:33], v[8:9], off offset:1024
	global_load_dwordx4 v[26:29], v[10:11], off offset:1024
	global_load_dwordx4 v[22:25], v[12:13], off offset:1024
	global_load_dwordx4 v[18:21], v[14:15], off offset:1024
	s_nop 0
	global_load_dwordx4 v[14:17], v[16:17], off offset:1024
	s_nop 0
	global_load_dwordx4 v[10:13], v[96:97], off offset:1024
	global_load_dwordx4 v[6:9], v[98:99], off offset:1024
	s_waitcnt vmcnt(15)
	v_pk_mul_f32 v[96:97], v[66:67], v[88:89]
	v_pk_mul_f32 v[98:99], v[68:69], v[90:91]
	v_add_f32_e32 v0, v96, v97
	v_add_f32_e32 v0, v98, v0
	s_waitcnt vmcnt(14)
	v_pk_mul_f32 v[96:97], v[62:63], v[88:89]
	v_pk_mul_f32 v[100:101], v[64:65], v[90:91]
	v_add_f32_e32 v96, v96, v97
	v_add_f32_e32 v0, v99, v0
	v_add_f32_e32 v96, v100, v96
	v_add_f32_e32 v96, v101, v96
	v_add_f32_dpp v0, v0, v0 quad_perm:[1,0,3,2] row_mask:0xf bank_mask:0xf bound_ctrl:1
	s_waitcnt vmcnt(13)
	v_pk_mul_f32 v[102:103], v[58:59], v[88:89]
	s_waitcnt vmcnt(12)
	v_pk_mul_f32 v[106:107], v[54:55], v[88:89]
	v_add_f32_dpp v0, v0, v0 quad_perm:[2,3,0,1] row_mask:0xf bank_mask:0xf bound_ctrl:1
	v_add_f32_dpp v96, v96, v96 quad_perm:[1,0,3,2] row_mask:0xf bank_mask:0xf bound_ctrl:1
	v_pk_mul_f32 v[104:105], v[60:61], v[90:91]
	v_pk_mul_f32 v[124:125], v[56:57], v[90:91]
	v_add_f32_dpp v118, v0, v0 row_half_mirror row_mask:0xf bank_mask:0xf bound_ctrl:1
	v_add_f32_dpp v0, v96, v96 quad_perm:[2,3,0,1] row_mask:0xf bank_mask:0xf bound_ctrl:1
	v_mov_b32_e32 v96, v106
	v_mov_b32_e32 v97, v102
	v_mov_b32_e32 v102, v107
	v_pk_add_f32 v[96:97], v[96:97], v[102:103]
	v_mov_b32_e32 v98, v124
	v_mov_b32_e32 v99, v104
	s_waitcnt vmcnt(11)
	v_pk_mul_f32 v[126:127], v[50:51], v[88:89]
	s_waitcnt vmcnt(10)
	v_pk_mul_f32 v[100:101], v[46:47], v[88:89]
	s_waitcnt vmcnt(9)
	v_pk_mul_f32 v[132:133], v[42:43], v[88:89]
	s_waitcnt vmcnt(8)
	v_pk_mul_f32 v[136:137], v[38:39], v[88:89]
	v_pk_add_f32 v[96:97], v[98:99], v[96:97]
	v_mov_b32_e32 v104, v125
	v_pk_mul_f32 v[128:129], v[52:53], v[90:91]
	v_pk_mul_f32 v[130:131], v[48:49], v[90:91]
	v_pk_mul_f32 v[134:135], v[44:45], v[90:91]
	v_pk_mul_f32 v[138:139], v[40:41], v[90:91]
	v_pk_add_f32 v[96:97], v[104:105], v[96:97]
	v_mov_b32_e32 v102, v100
	v_mov_b32_e32 v103, v126
	v_mov_b32_e32 v126, v101
	v_mov_b32_e32 v104, v136
	v_mov_b32_e32 v105, v132
	v_mov_b32_e32 v132, v137
	v_pk_add_f32 v[100:101], v[102:103], v[126:127]
	v_mov_b32_e32 v102, v130
	v_mov_b32_e32 v103, v128
	v_pk_add_f32 v[104:105], v[104:105], v[132:133]
	v_mov_b32_e32 v106, v138
	v_mov_b32_e32 v107, v134
	v_pk_add_f32 v[100:101], v[102:103], v[100:101]
	v_mov_b32_e32 v128, v131
	v_pk_add_f32 v[104:105], v[106:107], v[104:105]
	v_mov_b32_e32 v134, v139
	v_pk_add_f32 v[100:101], v[128:129], v[100:101]
	v_pk_add_f32 v[104:105], v[134:135], v[104:105]
	v_mov_b32_dpp v99, v97 quad_perm:[1,0,3,2] row_mask:0xf bank_mask:0xf bound_ctrl:1
	v_mov_b32_dpp v98, v96 quad_perm:[1,0,3,2] row_mask:0xf bank_mask:0xf bound_ctrl:1
	v_mov_b32_dpp v103, v101 quad_perm:[1,0,3,2] row_mask:0xf bank_mask:0xf bound_ctrl:1
	v_mov_b32_dpp v102, v100 quad_perm:[1,0,3,2] row_mask:0xf bank_mask:0xf bound_ctrl:1
	v_mov_b32_dpp v107, v105 quad_perm:[1,0,3,2] row_mask:0xf bank_mask:0xf bound_ctrl:1
	v_mov_b32_dpp v106, v104 quad_perm:[1,0,3,2] row_mask:0xf bank_mask:0xf bound_ctrl:1
	v_pk_add_f32 v[96:97], v[96:97], v[98:99]
	v_pk_add_f32 v[100:101], v[100:101], v[102:103]
	v_pk_add_f32 v[104:105], v[104:105], v[106:107]
	v_mov_b32_dpp v99, v97 quad_perm:[2,3,0,1] row_mask:0xf bank_mask:0xf bound_ctrl:1
	v_mov_b32_dpp v98, v96 quad_perm:[2,3,0,1] row_mask:0xf bank_mask:0xf bound_ctrl:1
	v_mov_b32_dpp v103, v101 quad_perm:[2,3,0,1] row_mask:0xf bank_mask:0xf bound_ctrl:1
	v_mov_b32_dpp v102, v100 quad_perm:[2,3,0,1] row_mask:0xf bank_mask:0xf bound_ctrl:1
	v_mov_b32_dpp v107, v105 quad_perm:[2,3,0,1] row_mask:0xf bank_mask:0xf bound_ctrl:1
	v_mov_b32_dpp v106, v104 quad_perm:[2,3,0,1] row_mask:0xf bank_mask:0xf bound_ctrl:1
	v_pk_add_f32 v[96:97], v[96:97], v[98:99]
	v_pk_add_f32 v[100:101], v[100:101], v[102:103]
	v_pk_add_f32 v[104:105], v[104:105], v[106:107]
	v_mov_b32_dpp v99, v97 row_half_mirror row_mask:0xf bank_mask:0xf bound_ctrl:1
	v_mov_b32_dpp v98, v96 row_half_mirror row_mask:0xf bank_mask:0xf bound_ctrl:1
	v_mov_b32_dpp v103, v101 row_half_mirror row_mask:0xf bank_mask:0xf bound_ctrl:1
	v_mov_b32_dpp v102, v100 row_half_mirror row_mask:0xf bank_mask:0xf bound_ctrl:1
	v_mov_b32_dpp v107, v105 row_half_mirror row_mask:0xf bank_mask:0xf bound_ctrl:1
	v_mov_b32_dpp v106, v104 row_half_mirror row_mask:0xf bank_mask:0xf bound_ctrl:1
	v_add_f32_dpp v120, v0, v0 row_half_mirror row_mask:0xf bank_mask:0xf bound_ctrl:1
	v_pk_add_f32 v[96:97], v[96:97], v[98:99]
	v_pk_add_f32 v[100:101], v[100:101], v[102:103]
	v_pk_add_f32 v[104:105], v[104:105], v[106:107]
	v_mov_b32_dpp v119, v118 row_mirror row_mask:0xf bank_mask:0xf bound_ctrl:1
	v_mov_b32_dpp v121, v120 row_mirror row_mask:0xf bank_mask:0xf bound_ctrl:1
	v_mov_b32_dpp v99, v97 row_mirror row_mask:0xf bank_mask:0xf bound_ctrl:1
	v_mov_b32_dpp v98, v96 row_mirror row_mask:0xf bank_mask:0xf bound_ctrl:1
	v_mov_b32_dpp v103, v101 row_mirror row_mask:0xf bank_mask:0xf bound_ctrl:1
	v_mov_b32_dpp v102, v100 row_mirror row_mask:0xf bank_mask:0xf bound_ctrl:1
	v_mov_b32_dpp v107, v105 row_mirror row_mask:0xf bank_mask:0xf bound_ctrl:1
	v_mov_b32_dpp v106, v104 row_mirror row_mask:0xf bank_mask:0xf bound_ctrl:1
	s_and_saveexec_b64 s[28:29], s[54:55]
	s_cbranch_execz .LBB0_379
	s_waitcnt vmcnt(0)
	v_add_u32_e32 v0, 7, v112
	v_lshl_add_u32 v0, v0, v111, v85
	v_cmp_lt_i32_e32 vcc, 7, v0
	s_and_saveexec_b64 s[30:31], vcc
	s_cbranch_execz .LBB0_383
	v_add_u32_e32 v0, -8, v0
	v_lshlrev_b64 v[124:125], 11, v[0:1]
	v_lshl_add_u64 v[124:125], v[94:95], 0, v[124:125]
	global_store_dwordx4 v[124:125], v[66:69], off
	s_nop 0
	global_store_dwordx4 v[124:125], v[34:37], off offset:1024
.LBB0_383:
	s_or_b64 exec, exec, s[30:31]
	v_add_u32_e32 v0, 6, v112
	v_lshl_add_u32 v0, v0, v111, v85
	v_cmp_lt_u32_e32 vcc, v123, v73
	v_cmp_lt_i32_e64 s[48:49], 7, v0
	s_and_b64 s[14:15], vcc, s[48:49]
	s_and_saveexec_b64 s[30:31], s[14:15]
	s_cbranch_execz .LBB0_385
	v_add_u32_e32 v0, -8, v0
	v_lshlrev_b64 v[66:67], 11, v[0:1]
	v_lshl_add_u64 v[66:67], v[94:95], 0, v[66:67]
	global_store_dwordx4 v[66:67], v[62:65], off
	s_nop 0
	global_store_dwordx4 v[66:67], v[30:33], off offset:1024
.LBB0_385:
	s_or_b64 exec, exec, s[30:31]
	v_add_u32_e32 v0, 5, v112
	v_lshl_add_u32 v0, v0, v111, v85
	v_cmp_lt_u32_e32 vcc, v122, v73
	v_cmp_lt_i32_e64 s[48:49], 7, v0
	s_and_b64 s[14:15], vcc, s[48:49]
	s_and_saveexec_b64 s[30:31], s[14:15]
	s_cbranch_execz .LBB0_387
	v_add_u32_e32 v0, -8, v0
	v_lshlrev_b64 v[62:63], 11, v[0:1]
	v_lshl_add_u64 v[62:63], v[94:95], 0, v[62:63]
	global_store_dwordx4 v[62:63], v[58:61], off
	s_nop 0
	global_store_dwordx4 v[62:63], v[26:29], off offset:1024
.LBB0_387:
	s_or_b64 exec, exec, s[30:31]
	v_add_u32_e32 v0, 4, v112
	v_lshl_add_u32 v0, v0, v111, v85
	v_cmp_lt_u32_e32 vcc, v117, v73
	v_cmp_lt_i32_e64 s[48:49], 7, v0
	s_and_b64 s[14:15], vcc, s[48:49]
	s_and_saveexec_b64 s[30:31], s[14:15]
	s_cbranch_execz .LBB0_389
	v_add_u32_e32 v0, -8, v0
	v_lshlrev_b64 v[58:59], 11, v[0:1]
	v_lshl_add_u64 v[58:59], v[94:95], 0, v[58:59]
	global_store_dwordx4 v[58:59], v[54:57], off
	s_nop 0
	global_store_dwordx4 v[58:59], v[22:25], off offset:1024
.LBB0_389:
	s_or_b64 exec, exec, s[30:31]
	v_add_u32_e32 v0, 3, v112
	v_lshl_add_u32 v0, v0, v111, v85
	v_cmp_lt_u32_e32 vcc, v116, v73
	v_cmp_lt_i32_e64 s[48:49], 7, v0
	s_and_b64 s[14:15], vcc, s[48:49]
	s_and_saveexec_b64 s[30:31], s[14:15]
	s_cbranch_execz .LBB0_391
	v_add_u32_e32 v0, -8, v0
	v_lshlrev_b64 v[54:55], 11, v[0:1]
	v_lshl_add_u64 v[54:55], v[94:95], 0, v[54:55]
	global_store_dwordx4 v[54:55], v[50:53], off
	s_nop 0
	global_store_dwordx4 v[54:55], v[18:21], off offset:1024
.LBB0_391:
	s_or_b64 exec, exec, s[30:31]
	v_add_u32_e32 v0, 2, v112
	v_lshl_add_u32 v0, v0, v111, v85
	v_cmp_lt_u32_e32 vcc, v115, v73
	v_cmp_lt_i32_e64 s[48:49], 7, v0
	s_and_b64 s[14:15], vcc, s[48:49]
	s_and_saveexec_b64 s[30:31], s[14:15]
	s_cbranch_execz .LBB0_393
	v_add_u32_e32 v0, -8, v0
	v_lshlrev_b64 v[50:51], 11, v[0:1]
	v_lshl_add_u64 v[50:51], v[94:95], 0, v[50:51]
	global_store_dwordx4 v[50:51], v[46:49], off
	s_nop 0
	global_store_dwordx4 v[50:51], v[14:17], off offset:1024
.LBB0_393:
	s_or_b64 exec, exec, s[30:31]
	v_add_u32_e32 v0, 1, v112
	v_lshl_add_u32 v0, v0, v111, v85
	v_cmp_lt_u32_e32 vcc, v114, v73
	v_cmp_lt_i32_e64 s[48:49], 7, v0
	s_and_b64 s[14:15], vcc, s[48:49]
	s_and_saveexec_b64 s[30:31], s[14:15]
	s_cbranch_execz .LBB0_395
	v_add_u32_e32 v0, -8, v0
	v_lshlrev_b64 v[46:47], 11, v[0:1]
	v_lshl_add_u64 v[46:47], v[94:95], 0, v[46:47]
	global_store_dwordx4 v[46:47], v[42:45], off
	s_nop 0
	global_store_dwordx4 v[46:47], v[10:13], off offset:1024
.LBB0_395:
	s_or_b64 exec, exec, s[30:31]
	v_lshl_add_u32 v0, v112, v111, v85
	v_cmp_lt_u32_e32 vcc, v113, v73
	v_cmp_lt_i32_e64 s[48:49], 7, v0
	s_and_b64 s[14:15], vcc, s[48:49]
	s_and_b64 exec, exec, s[14:15]
	s_cbranch_execz .Lsm_nw1
	v_add_u32_e32 v0, -8, v0
	v_lshlrev_b64 v[42:43], 11, v[0:1]
	v_lshl_add_u64 v[42:43], v[94:95], 0, v[42:43]
	global_store_dwordx4 v[42:43], v[38:41], off
	s_nop 0
	global_store_dwordx4 v[42:43], v[6:9], off offset:1024
